# C + nt on final-output stores in P15
# baseline (speedup 1.0000x reference)
.LBB0_1877:
	s_or_b64 exec, exec, s[0:1]
	v_ashrrev_i32_e32 v115, 31, v114
	v_lshl_add_u64 v[2:3], v[114:115], 4, s[6:7]
	s_barrier
	global_load_dword v4, v[2:3], off sc1
	global_load_dword v6, v[2:3], off offset:4 sc1
	global_load_dword v5, v[2:3], off offset:8 sc1
	global_load_dword v7, v[2:3], off offset:12 sc1
	v_add_u32_e32 v2, 16, v114
	v_ashrrev_i32_e32 v3, 31, v2
	v_lshl_add_u64 v[2:3], v[2:3], 4, s[6:7]
	global_load_dword v8, v[2:3], off sc1
	global_load_dword v12, v[2:3], off offset:4 sc1
	global_load_dword v9, v[2:3], off offset:8 sc1
	global_load_dword v13, v[2:3], off offset:12 sc1
	v_add_u32_e32 v2, 32, v114
	v_ashrrev_i32_e32 v3, 31, v2
	v_lshl_add_u64 v[2:3], v[2:3], 4, s[6:7]
	global_load_dword v14, v[2:3], off sc1
	global_load_dword v16, v[2:3], off offset:4 sc1
	global_load_dword v15, v[2:3], off offset:8 sc1
	global_load_dword v17, v[2:3], off offset:12 sc1
	v_add_u32_e32 v2, 48, v114
	v_add_u32_e32 v18, 0x80, v114
	v_ashrrev_i32_e32 v3, 31, v2
	v_ashrrev_i32_e32 v19, 31, v18
	v_lshl_add_u64 v[2:3], v[2:3], 4, s[6:7]
	v_lshl_add_u64 v[18:19], v[18:19], 4, s[6:7]
	global_load_dword v20, v[2:3], off sc1
	global_load_dword v22, v[2:3], off offset:4 sc1
	global_load_dword v21, v[2:3], off offset:8 sc1
	global_load_dword v23, v[2:3], off offset:12 sc1
	s_nop 0
	global_load_dword v2, v[18:19], off sc1
	global_load_dword v24, v[18:19], off offset:4 sc1
	global_load_dword v3, v[18:19], off offset:8 sc1
	global_load_dword v25, v[18:19], off offset:12 sc1
	v_mov_b32_e32 v11, 0x358637bd
	s_mov_b32 s14, 0xf800000
	v_mov_b32_e32 v1, 0x260
	s_waitcnt vmcnt(16)
	v_pk_add_f32 v[4:5], v[4:5], v[6:7]
	s_nop 0
	v_add_f32_e32 v10, v4, v5
	s_waitcnt vmcnt(12)
	v_pk_add_f32 v[4:5], v[8:9], v[12:13]
	v_fmamk_f32 v8, v10, 0x3a800000, v11
	v_add_f32_e32 v4, v4, v5
	v_cmp_gt_f32_e32 vcc, s14, v8
	s_waitcnt vmcnt(8)
	v_pk_add_f32 v[6:7], v[14:15], v[16:17]
	v_fmamk_f32 v4, v4, 0x3a800000, v11
	v_add_f32_e32 v5, v6, v7
	v_mul_f32_e32 v6, 0x4f800000, v8
	v_cndmask_b32_e32 v6, v8, v6, vcc
	v_mul_f32_e32 v7, 0x4f800000, v4
	v_sqrt_f32_e32 v9, v6
	v_cmp_gt_f32_e64 s[0:1], s14, v4
	v_fmamk_f32 v5, v5, 0x3a800000, v11
	v_mul_f32_e32 v8, 0x4f800000, v5
	v_cndmask_b32_e64 v4, v4, v7, s[0:1]
	v_sqrt_f32_e32 v7, v4
	v_add_u32_e32 v10, -1, v9
	v_add_u32_e32 v12, 1, v9
	v_fma_f32 v13, -v10, v9, v6
	v_fma_f32 v14, -v12, v9, v6
	v_add_u32_e32 v15, -1, v7
	v_cmp_ge_f32_e64 s[4:5], 0, v13
	v_add_u32_e32 v16, 1, v7
	v_fma_f32 v13, -v16, v7, v4
	v_cndmask_b32_e64 v9, v9, v10, s[4:5]
	v_fma_f32 v10, -v15, v7, v4
	v_cmp_lt_f32_e64 s[4:5], 0, v14
	v_cmp_gt_f32_e64 s[2:3], s14, v5
	s_waitcnt vmcnt(0)
	v_pk_add_f32 v[2:3], v[2:3], v[24:25]
	v_cndmask_b32_e64 v9, v9, v12, s[4:5]
	v_cmp_ge_f32_e64 s[4:5], 0, v10
	v_mul_f32_e32 v10, 0x37800000, v9
	v_cndmask_b32_e32 v9, v9, v10, vcc
	v_cndmask_b32_e64 v7, v7, v15, s[4:5]
	v_cmp_lt_f32_e64 s[4:5], 0, v13
	v_cmp_class_f32_e32 vcc, v6, v1
	v_cndmask_b32_e64 v5, v5, v8, s[2:3]
	v_cndmask_b32_e64 v7, v7, v16, s[4:5]
	v_mul_f32_e32 v10, 0x37800000, v7
	v_cndmask_b32_e32 v6, v9, v6, vcc
	v_cndmask_b32_e64 v7, v7, v10, s[0:1]
	v_div_scale_f32 v9, s[0:1], v6, v6, 1.0
	v_cmp_class_f32_e64 s[0:1], v4, v1
	v_div_scale_f32 v10, vcc, 1.0, v6, 1.0
	s_nop 0
	v_cndmask_b32_e64 v4, v7, v4, s[0:1]
	v_rcp_f32_e32 v7, v9
	v_div_scale_f32 v12, s[0:1], v4, v4, 1.0
	v_rcp_f32_e32 v13, v12
	v_fma_f32 v15, -v9, v7, 1.0
	v_fmac_f32_e32 v7, v15, v7
	v_sqrt_f32_e32 v8, v5
	v_fma_f32 v15, -v12, v13, 1.0
	v_mul_f32_e32 v16, v10, v7
	v_div_scale_f32 v14, s[0:1], 1.0, v4, 1.0
	v_fmac_f32_e32 v13, v15, v13
	v_fma_f32 v15, -v9, v16, v10
	v_mul_f32_e32 v18, v14, v13
	v_fmac_f32_e32 v16, v15, v7
	v_fma_f32 v15, -v12, v18, v14
	v_fma_f32 v9, -v9, v16, v10
	v_add_u32_e32 v17, -1, v8
	v_fmac_f32_e32 v18, v15, v13
	v_div_fmas_f32 v7, v9, v7, v16
	v_fma_f32 v9, -v12, v18, v14
	v_div_fixup_f32 v12, v7, v6, 1.0
	v_fma_f32 v6, -v17, v8, v5
	v_cmp_ge_f32_e32 vcc, 0, v6
	v_add_u32_e32 v7, 1, v8
	v_add_f32_e32 v2, v2, v3
	v_cndmask_b32_e32 v6, v8, v17, vcc
	v_fma_f32 v8, -v7, v8, v5
	v_cmp_lt_f32_e32 vcc, 0, v8
	s_lshl_b64 s[4:5], s[12:13], 2
	s_nop 0
	v_cndmask_b32_e32 v6, v6, v7, vcc
	v_mul_f32_e32 v7, 0x37800000, v6
	v_cndmask_b32_e64 v6, v6, v7, s[2:3]
	v_cmp_class_f32_e32 vcc, v5, v1
	s_nop 1
	v_cndmask_b32_e32 v14, v6, v5, vcc
	v_add_u32_e32 v6, 0x90, v114
	v_ashrrev_i32_e32 v7, 31, v6
	s_mov_b64 vcc, s[0:1]
	v_lshl_add_u64 v[6:7], v[6:7], 4, s[6:7]
	v_div_fmas_f32 v5, v9, v13, v18
	global_load_dword v8, v[6:7], off sc1
	global_load_dword v18, v[6:7], off offset:4 sc1
	global_load_dword v9, v[6:7], off offset:8 sc1
	global_load_dword v19, v[6:7], off offset:12 sc1
	v_div_scale_f32 v15, s[2:3], v14, v14, 1.0
	v_rcp_f32_e32 v16, v15
	v_div_fixup_f32 v10, v5, v4, 1.0
	v_div_scale_f32 v13, vcc, 1.0, v14, 1.0
	v_fma_f32 v4, -v15, v16, 1.0
	v_fmac_f32_e32 v16, v4, v16
	v_pk_add_f32 v[4:5], v[20:21], v[22:23]
	v_mul_f32_e32 v17, v13, v16
	v_add_f32_e32 v4, v4, v5
	v_fmamk_f32 v4, v4, 0x3a800000, v11
	v_mul_f32_e32 v5, 0x4f800000, v4
	v_cmp_gt_f32_e64 s[0:1], s14, v4
	v_fma_f32 v6, -v15, v17, v13
	v_fmac_f32_e32 v17, v6, v16
	v_cndmask_b32_e64 v4, v4, v5, s[0:1]
	v_sqrt_f32_e32 v5, v4
	v_fma_f32 v6, -v15, v17, v13
	v_fmamk_f32 v15, v2, 0x3a800000, v11
	v_add_u32_e32 v2, 0xa0, v114
	v_add_u32_e32 v7, -1, v5
	v_fma_f32 v13, -v7, v5, v4
	v_cmp_ge_f32_e64 s[2:3], 0, v13
	v_add_u32_e32 v13, 1, v5
	v_ashrrev_i32_e32 v3, 31, v2
	v_cndmask_b32_e64 v7, v5, v7, s[2:3]
	v_fma_f32 v5, -v13, v5, v4
	v_cmp_lt_f32_e64 s[2:3], 0, v5
	v_div_fmas_f32 v6, v6, v16, v17
	v_mul_f32_e32 v16, 0x4f800000, v15
	v_cndmask_b32_e64 v5, v7, v13, s[2:3]
	v_mul_f32_e32 v7, 0x37800000, v5
	v_cndmask_b32_e64 v5, v5, v7, s[0:1]
	v_cmp_class_f32_e64 s[0:1], v4, v1
	v_lshl_add_u64 v[2:3], v[2:3], 4, s[6:7]
	v_div_fixup_f32 v14, v6, v14, 1.0
	v_cndmask_b32_e64 v4, v5, v4, s[0:1]
	v_div_scale_f32 v5, s[0:1], v4, v4, 1.0
	v_rcp_f32_e32 v7, v5
	v_cmp_gt_f32_e64 s[0:1], s14, v15
	global_load_dword v20, v[2:3], off sc1
	global_load_dword v22, v[2:3], off offset:4 sc1
	global_load_dword v21, v[2:3], off offset:8 sc1
	global_load_dword v23, v[2:3], off offset:12 sc1
	v_cndmask_b32_e64 v2, v15, v16, s[0:1]
	v_fma_f32 v6, -v5, v7, 1.0
	v_fmac_f32_e32 v7, v6, v7
	v_div_scale_f32 v6, vcc, 1.0, v4, 1.0
	v_sqrt_f32_e32 v3, v2
	v_mul_f32_e32 v13, v6, v7
	v_fma_f32 v15, -v5, v13, v6
	v_fmac_f32_e32 v13, v15, v7
	v_fma_f32 v5, -v5, v13, v6
	v_add_u32_e32 v6, -1, v3
	v_fma_f32 v15, -v6, v3, v2
	v_cmp_ge_f32_e64 s[2:3], 0, v15
	v_add_u32_e32 v15, 1, v3
	s_waitcnt vmcnt(0)
	v_pk_add_f32 v[20:21], v[20:21], v[22:23]
	v_cndmask_b32_e64 v6, v3, v6, s[2:3]
	v_fma_f32 v3, -v15, v3, v2
	v_cmp_lt_f32_e64 s[2:3], 0, v3
	v_add_f32_e32 v20, v20, v21
	v_fmamk_f32 v20, v20, 0x3a800000, v11
	v_cndmask_b32_e64 v3, v6, v15, s[2:3]
	v_mul_f32_e32 v6, 0x37800000, v3
	v_cndmask_b32_e64 v3, v3, v6, s[0:1]
	v_cmp_class_f32_e64 s[0:1], v2, v1
	v_mul_f32_e32 v21, 0x4f800000, v20
	s_nop 0
	v_cndmask_b32_e64 v6, v3, v2, s[0:1]
	v_div_scale_f32 v15, s[0:1], v6, v6, 1.0
	v_rcp_f32_e32 v17, v15
	v_div_fmas_f32 v2, v5, v7, v13
	v_div_fixup_f32 v16, v2, v4, 1.0
	v_div_scale_f32 v4, vcc, 1.0, v6, 1.0
	v_fma_f32 v2, -v15, v17, 1.0
	v_fmac_f32_e32 v17, v2, v17
	v_add_u32_e32 v2, 0xb0, v114
	v_ashrrev_i32_e32 v3, 31, v2
	v_lshl_add_u64 v[2:3], v[2:3], 4, s[6:7]
	global_load_dword v24, v[2:3], off sc1
	global_load_dword v28, v[2:3], off offset:4 sc1
	global_load_dword v25, v[2:3], off offset:8 sc1
	global_load_dword v29, v[2:3], off offset:12 sc1
	v_pk_add_f32 v[2:3], v[8:9], v[18:19]
	v_mul_f32_e32 v5, v4, v17
	v_add_f32_e32 v2, v2, v3
	v_fmamk_f32 v2, v2, 0x3a800000, v11
	v_mul_f32_e32 v3, 0x4f800000, v2
	v_cmp_gt_f32_e64 s[0:1], s14, v2
	v_fma_f32 v7, -v15, v5, v4
	v_fmac_f32_e32 v5, v7, v17
	v_cndmask_b32_e64 v2, v2, v3, s[0:1]
	v_sqrt_f32_e32 v3, v2
	v_fma_f32 v4, -v15, v5, v4
	s_add_i32 s6, s24, s25
	v_add_u32_e32 v7, -1, v3
	v_fma_f32 v8, -v7, v3, v2
	v_cmp_ge_f32_e64 s[2:3], 0, v8
	v_add_u32_e32 v8, 1, v3
	v_add_u32_e32 v32, s6, v245
	v_cndmask_b32_e64 v7, v3, v7, s[2:3]
	v_fma_f32 v3, -v8, v3, v2
	v_cmp_lt_f32_e64 s[2:3], 0, v3
	v_lshlrev_b32_e32 v114, 3, v244
	v_ashrrev_i32_e32 v33, 31, v32
	v_cndmask_b32_e64 v3, v7, v8, s[2:3]
	v_mul_f32_e32 v7, 0x37800000, v3
	v_cndmask_b32_e64 v3, v3, v7, s[0:1]
	v_cmp_class_f32_e64 s[0:1], v2, v1
	v_ashrrev_i32_e32 v115, 31, v114
	v_lshlrev_b64 v[32:33], 12, v[32:33]
	v_cndmask_b32_e64 v13, v3, v2, s[0:1]
	v_div_scale_f32 v15, s[0:1], v13, v13, 1.0
	v_rcp_f32_e32 v19, v15
	v_div_fmas_f32 v2, v4, v17, v5
	v_div_fixup_f32 v18, v2, v6, 1.0
	s_add_u32 s0, s8, s4
	v_fma_f32 v2, -v15, v19, 1.0
	v_fmac_f32_e32 v19, v2, v19
	v_add_u32_e32 v2, s16, v242
	s_addc_u32 s1, s9, s5
	v_ashrrev_i32_e32 v3, 31, v2
	v_lshl_add_u64 v[26:27], v[2:3], 2, s[0:1]
	global_load_dwordx4 v[2:5], v[26:27], off offset:16
	global_load_dwordx4 v[6:9], v[26:27], off
	v_cmp_gt_f32_e64 s[0:1], s14, v20
	v_div_scale_f32 v17, vcc, 1.0, v13, 1.0
	s_nop 0
	v_cndmask_b32_e64 v20, v20, v21, s[0:1]
	v_sqrt_f32_e32 v21, v20
	v_mul_f32_e32 v30, v17, v19
	v_fma_f32 v22, -v15, v30, v17
	v_fmac_f32_e32 v30, v22, v19
	v_fma_f32 v15, -v15, v30, v17
	v_add_u32_e32 v17, -1, v21
	v_fma_f32 v22, -v17, v21, v20
	v_cmp_ge_f32_e64 s[2:3], 0, v22
	v_add_u32_e32 v22, 1, v21
	v_div_fmas_f32 v15, v15, v19, v30
	v_cndmask_b32_e64 v17, v21, v17, s[2:3]
	v_fma_f32 v21, -v22, v21, v20
	v_cmp_lt_f32_e64 s[2:3], 0, v21
	s_nop 1
	v_cndmask_b32_e64 v17, v17, v22, s[2:3]
	v_mul_f32_e32 v21, 0x37800000, v17
	v_cndmask_b32_e64 v17, v17, v21, s[0:1]
	v_cmp_class_f32_e64 s[0:1], v20, v1
	v_div_fixup_f32 v22, v15, v13, 1.0
	s_nop 0
	v_cndmask_b32_e64 v17, v17, v20, s[0:1]
	v_div_scale_f32 v23, s[0:1], v17, v17, 1.0
	v_rcp_f32_e32 v31, v23
	s_waitcnt vmcnt(2)
	v_pk_add_f32 v[20:21], v[24:25], v[28:29]
	s_nop 0
	v_add_f32_e32 v19, v20, v21
	v_fmac_f32_e32 v11, 0x3a800000, v19
	v_mul_f32_e32 v19, 0x4f800000, v11
	v_cmp_gt_f32_e64 s[0:1], s14, v11
	v_fma_f32 v13, -v23, v31, 1.0
	v_fmac_f32_e32 v31, v13, v31
	v_cndmask_b32_e64 v11, v11, v19, s[0:1]
	v_sqrt_f32_e32 v19, v11
	v_div_scale_f32 v13, vcc, 1.0, v17, 1.0
	v_mul_f32_e32 v15, v13, v31
	v_fma_f32 v20, -v23, v15, v13
	v_fmac_f32_e32 v15, v20, v31
	v_add_u32_e32 v20, -1, v19
	v_fma_f32 v21, -v20, v19, v11
	v_cmp_ge_f32_e64 s[2:3], 0, v21
	v_add_u32_e32 v21, 1, v19
	v_fma_f32 v13, -v23, v15, v13
	v_cndmask_b32_e64 v20, v19, v20, s[2:3]
	v_fma_f32 v19, -v21, v19, v11
	v_cmp_lt_f32_e64 s[2:3], 0, v19
	v_div_fmas_f32 v13, v13, v31, v15
	v_div_fixup_f32 v24, v13, v17, 1.0
	v_cndmask_b32_e64 v19, v20, v21, s[2:3]
	v_mul_f32_e32 v20, 0x37800000, v19
	v_cndmask_b32_e64 v19, v19, v20, s[0:1]
	v_cmp_class_f32_e64 s[0:1], v11, v1
	s_nop 1
	v_cndmask_b32_e64 v1, v19, v11, s[0:1]
	v_div_scale_f32 v11, s[0:1], v1, v1, 1.0
	v_rcp_f32_e32 v19, v11
	s_add_u32 s0, s10, s4
	s_addc_u32 s1, s11, s5
	s_lshl_b32 s2, s16, 2
	v_fma_f32 v13, -v11, v19, 1.0
	v_fmac_f32_e32 v19, v13, v19
	v_div_scale_f32 v13, vcc, 1.0, v1, 1.0
	s_add_u32 s0, s0, s2
	v_mul_f32_e32 v15, v13, v19
	s_addc_u32 s1, s1, 0
	v_fma_f32 v17, -v11, v15, v13
	v_pk_mul_f32 v[30:31], v[238:239], v[12:13] op_sel_hi:[1,0]
	v_pk_mul_f32 v[28:29], v[240:241], v[12:13] op_sel_hi:[1,0]
	v_lshl_add_u64 v[114:115], v[114:115], 2, s[0:1]
	v_fmac_f32_e32 v15, v17, v19
	s_waitcnt vmcnt(0)
	v_pk_mul_f32 v[28:29], v[28:29], v[6:7]
	v_pk_mul_f32 v[30:31], v[30:31], v[8:9]
	v_lshl_add_u64 v[32:33], v[114:115], 0, v[32:33]
	v_fma_f32 v11, -v11, v15, v13
	global_store_dwordx4 v[32:33], v[28:31], off nt
	v_div_fmas_f32 v11, v11, v19, v15
	s_mov_b32 s0, 0x10000
	v_pk_mul_f32 v[30:31], v[234:235], v[12:13] op_sel_hi:[1,0]
	v_pk_mul_f32 v[28:29], v[236:237], v[12:13] op_sel_hi:[1,0]
	v_pk_mul_f32 v[30:31], v[30:31], v[4:5]
	v_pk_mul_f32 v[28:29], v[28:29], v[2:3]
	global_store_dwordx4 v[32:33], v[28:31], off offset:16 nt
	v_div_fixup_f32 v20, v11, v1, 1.0
	s_nop 0
	v_pk_mul_f32 v[28:29], v[110:111], v[10:11] op_sel_hi:[1,0]
	v_pk_mul_f32 v[30:31], v[112:113], v[10:11] op_sel_hi:[1,0]
	v_add_co_u32_e32 v110, vcc, s0, v32
	v_pk_mul_f32 v[30:31], v[30:31], v[8:9]
	v_pk_mul_f32 v[28:29], v[28:29], v[6:7]
	v_addc_co_u32_e32 v111, vcc, 0, v33, vcc
	global_store_dwordx4 v[110:111], v[28:31], off nt
	s_mov_b32 s0, 0x20000
	s_nop 0
	v_pk_mul_f32 v[28:29], v[106:107], v[10:11] op_sel_hi:[1,0]
	v_pk_mul_f32 v[30:31], v[108:109], v[10:11] op_sel_hi:[1,0]
	v_pk_mul_f32 v[28:29], v[28:29], v[2:3]
	v_pk_mul_f32 v[30:31], v[30:31], v[4:5]
	global_store_dwordx4 v[110:111], v[28:31], off offset:16 nt
	s_nop 1
	v_pk_mul_f32 v[28:29], v[94:95], v[14:15] op_sel_hi:[1,0]
	v_pk_mul_f32 v[30:31], v[96:97], v[14:15] op_sel_hi:[1,0]
	v_add_co_u32_e32 v94, vcc, s0, v32
	v_pk_mul_f32 v[30:31], v[30:31], v[8:9]
	v_pk_mul_f32 v[28:29], v[28:29], v[6:7]
	v_addc_co_u32_e32 v95, vcc, 0, v33, vcc
	global_store_dwordx4 v[94:95], v[28:31], off nt
	s_mov_b32 s0, 0x30000
	s_nop 0
	v_pk_mul_f32 v[28:29], v[90:91], v[14:15] op_sel_hi:[1,0]
	v_pk_mul_f32 v[30:31], v[92:93], v[14:15] op_sel_hi:[1,0]
	v_pk_mul_f32 v[28:29], v[28:29], v[2:3]
	v_pk_mul_f32 v[30:31], v[30:31], v[4:5]
	global_store_dwordx4 v[94:95], v[28:31], off offset:16 nt
	s_nop 1
	v_pk_mul_f32 v[28:29], v[78:79], v[16:17] op_sel_hi:[1,0]
	v_pk_mul_f32 v[30:31], v[80:81], v[16:17] op_sel_hi:[1,0]
	v_add_co_u32_e32 v78, vcc, s0, v32
	v_pk_mul_f32 v[30:31], v[30:31], v[8:9]
	v_pk_mul_f32 v[28:29], v[28:29], v[6:7]
	v_addc_co_u32_e32 v79, vcc, 0, v33, vcc
	global_store_dwordx4 v[78:79], v[28:31], off nt
	s_mov_b32 s0, 0x80000
	s_nop 0
	v_pk_mul_f32 v[28:29], v[74:75], v[16:17] op_sel_hi:[1,0]
	v_pk_mul_f32 v[30:31], v[76:77], v[16:17] op_sel_hi:[1,0]
	v_pk_mul_f32 v[28:29], v[28:29], v[2:3]
	v_pk_mul_f32 v[30:31], v[30:31], v[4:5]
	global_store_dwordx4 v[78:79], v[28:31], off offset:16 nt
	v_add_co_u32_e32 v74, vcc, s0, v32
	s_nop 0
	v_pk_mul_f32 v[28:29], v[158:159], v[18:19] op_sel_hi:[1,0]
	v_pk_mul_f32 v[30:31], v[160:161], v[18:19] op_sel_hi:[1,0]
	v_pk_mul_f32 v[28:29], v[28:29], v[6:7]
	v_pk_mul_f32 v[30:31], v[30:31], v[8:9]
	v_addc_co_u32_e32 v75, vcc, 0, v33, vcc
	global_store_dwordx4 v[74:75], v[28:31], off nt
	s_mov_b32 s0, 0x90000
	v_add_co_u32_e32 v76, vcc, s0, v32
	v_pk_mul_f32 v[28:29], v[154:155], v[18:19] op_sel_hi:[1,0]
	v_pk_mul_f32 v[30:31], v[156:157], v[18:19] op_sel_hi:[1,0]
	v_pk_mul_f32 v[28:29], v[28:29], v[2:3]
	v_pk_mul_f32 v[30:31], v[30:31], v[4:5]
	global_store_dwordx4 v[74:75], v[28:31], off offset:16 nt
	v_addc_co_u32_e32 v77, vcc, 0, v33, vcc
	s_nop 0
	v_pk_mul_f32 v[28:29], v[146:147], v[22:23] op_sel_hi:[1,0]
	v_pk_mul_f32 v[30:31], v[148:149], v[22:23] op_sel_hi:[1,0]
	v_pk_mul_f32 v[28:29], v[6:7], v[28:29]
	v_pk_mul_f32 v[30:31], v[8:9], v[30:31]
	global_store_dwordx4 v[76:77], v[28:31], off nt
	s_mov_b32 s0, 0xa0000
	v_add_co_u32_e32 v80, vcc, s0, v32
	v_pk_mul_f32 v[28:29], v[138:139], v[22:23] op_sel_hi:[1,0]
	v_pk_mul_f32 v[30:31], v[140:141], v[22:23] op_sel_hi:[1,0]
	v_pk_mul_f32 v[28:29], v[28:29], v[2:3]
	v_pk_mul_f32 v[30:31], v[30:31], v[4:5]
	global_store_dwordx4 v[76:77], v[28:31], off offset:16 nt
	v_addc_co_u32_e32 v81, vcc, 0, v33, vcc
	s_nop 0
	v_pk_mul_f32 v[28:29], v[134:135], v[24:25] op_sel_hi:[1,0]
	v_pk_mul_f32 v[30:31], v[136:137], v[24:25] op_sel_hi:[1,0]
	v_pk_mul_f32 v[28:29], v[6:7], v[28:29]
	v_pk_mul_f32 v[30:31], v[8:9], v[30:31]
	global_store_dwordx4 v[80:81], v[28:31], off nt
	s_mov_b32 s0, 0xb0000
	s_nop 0
	v_pk_mul_f32 v[28:29], v[130:131], v[24:25] op_sel_hi:[1,0]
	v_pk_mul_f32 v[30:31], v[132:133], v[24:25] op_sel_hi:[1,0]
	v_pk_mul_f32 v[28:29], v[2:3], v[28:29]
	v_pk_mul_f32 v[30:31], v[4:5], v[30:31]
	global_store_dwordx4 v[80:81], v[28:31], off offset:16 nt
	s_nop 1
	v_pk_mul_f32 v[30:31], v[128:129], v[20:21] op_sel_hi:[1,0]
	v_pk_mul_f32 v[28:29], v[126:127], v[20:21] op_sel_hi:[1,0]
	v_pk_mul_f32 v[8:9], v[8:9], v[30:31]
	v_add_co_u32_e32 v30, vcc, s0, v32
	v_pk_mul_f32 v[6:7], v[6:7], v[28:29]
	s_nop 0
	v_addc_co_u32_e32 v31, vcc, 0, v33, vcc
	global_store_dwordx4 v[30:31], v[6:9], off nt
	v_pk_mul_f32 v[28:29], v[230:231], v[12:13] op_sel_hi:[1,0]
	s_nop 0
	v_pk_mul_f32 v[6:7], v[122:123], v[20:21] op_sel_hi:[1,0]
	v_pk_mul_f32 v[8:9], v[124:125], v[20:21] op_sel_hi:[1,0]
	v_pk_mul_f32 v[2:3], v[2:3], v[6:7]
	v_pk_mul_f32 v[4:5], v[4:5], v[8:9]
	global_store_dwordx4 v[30:31], v[2:5], off offset:16 nt
	global_load_dwordx4 v[2:5], v[26:27], off offset:512
	s_nop 0
	global_load_dwordx4 v[6:9], v[26:27], off offset:528
	v_pk_mul_f32 v[26:27], v[232:233], v[12:13] op_sel_hi:[1,0]
	s_waitcnt vmcnt(1)
	v_pk_mul_f32 v[28:29], v[28:29], v[4:5]
	v_pk_mul_f32 v[26:27], v[26:27], v[2:3]
	global_store_dwordx4 v[32:33], v[26:29], off offset:512 nt
	s_nop 1
	v_pk_mul_f32 v[28:29], v[250:251], v[12:13] op_sel_hi:[1,0]
	v_pk_mul_f32 v[12:13], v[228:229], v[12:13] op_sel_hi:[1,0]
	s_waitcnt vmcnt(1)
	v_pk_mul_f32 v[28:29], v[28:29], v[8:9]
	v_pk_mul_f32 v[26:27], v[12:13], v[6:7]
	v_pk_mul_f32 v[12:13], v[104:105], v[10:11] op_sel_hi:[1,0]
	global_store_dwordx4 v[32:33], v[26:29], off offset:528 nt
	s_nop 1
	v_pk_mul_f32 v[26:27], v[102:103], v[10:11] op_sel_hi:[1,0]
	v_pk_mul_f32 v[28:29], v[12:13], v[4:5]
	v_pk_mul_f32 v[12:13], v[100:101], v[10:11] op_sel_hi:[1,0]
	v_pk_mul_f32 v[10:11], v[98:99], v[10:11] op_sel_hi:[1,0]
	v_pk_mul_f32 v[12:13], v[12:13], v[8:9]
	v_pk_mul_f32 v[10:11], v[10:11], v[6:7]
	global_store_dwordx4 v[110:111], v[10:13], off offset:528 nt
	v_pk_mul_f32 v[26:27], v[26:27], v[2:3]
	global_store_dwordx4 v[110:111], v[26:29], off offset:512 nt
	v_pk_mul_f32 v[12:13], v[88:89], v[14:15] op_sel_hi:[1,0]
	v_pk_mul_f32 v[10:11], v[86:87], v[14:15] op_sel_hi:[1,0]
	v_pk_mul_f32 v[12:13], v[12:13], v[4:5]
	v_pk_mul_f32 v[10:11], v[10:11], v[2:3]
	global_store_dwordx4 v[94:95], v[10:13], off offset:512 nt
	s_nop 1
	v_pk_mul_f32 v[12:13], v[84:85], v[14:15] op_sel_hi:[1,0]
	v_pk_mul_f32 v[10:11], v[82:83], v[14:15] op_sel_hi:[1,0]
	v_pk_mul_f32 v[12:13], v[12:13], v[8:9]
	v_pk_mul_f32 v[10:11], v[10:11], v[6:7]
	global_store_dwordx4 v[94:95], v[10:13], off offset:528 nt
	s_nop 1
	v_pk_mul_f32 v[12:13], v[72:73], v[16:17] op_sel_hi:[1,0]
	v_pk_mul_f32 v[10:11], v[70:71], v[16:17] op_sel_hi:[1,0]
	v_pk_mul_f32 v[12:13], v[12:13], v[4:5]
	v_pk_mul_f32 v[10:11], v[10:11], v[2:3]
	global_store_dwordx4 v[78:79], v[10:13], off offset:512 nt
	s_nop 1
	v_pk_mul_f32 v[12:13], v[68:69], v[16:17] op_sel_hi:[1,0]
	v_pk_mul_f32 v[10:11], v[66:67], v[16:17] op_sel_hi:[1,0]
	v_pk_mul_f32 v[12:13], v[12:13], v[8:9]
	v_pk_mul_f32 v[10:11], v[10:11], v[6:7]
	global_store_dwordx4 v[78:79], v[10:13], off offset:528 nt
	s_nop 1
	v_pk_mul_f32 v[12:13], v[56:57], v[18:19] op_sel_hi:[1,0]
	v_pk_mul_f32 v[10:11], v[54:55], v[18:19] op_sel_hi:[1,0]
	v_pk_mul_f32 v[12:13], v[12:13], v[4:5]
	v_pk_mul_f32 v[10:11], v[10:11], v[2:3]
	global_store_dwordx4 v[74:75], v[10:13], off offset:512 nt
	s_nop 1
	v_pk_mul_f32 v[12:13], v[52:53], v[18:19] op_sel_hi:[1,0]
	v_pk_mul_f32 v[10:11], v[50:51], v[18:19] op_sel_hi:[1,0]
	v_pk_mul_f32 v[12:13], v[12:13], v[8:9]
	v_pk_mul_f32 v[10:11], v[10:11], v[6:7]
	global_store_dwordx4 v[74:75], v[10:13], off offset:528 nt
	s_nop 1
	v_pk_mul_f32 v[12:13], v[40:41], v[22:23] op_sel_hi:[1,0]
	v_pk_mul_f32 v[10:11], v[38:39], v[22:23] op_sel_hi:[1,0]
	v_pk_mul_f32 v[12:13], v[12:13], v[4:5]
	v_pk_mul_f32 v[10:11], v[10:11], v[2:3]
	global_store_dwordx4 v[76:77], v[10:13], off offset:512 nt
	s_nop 1
	v_pk_mul_f32 v[12:13], v[36:37], v[22:23] op_sel_hi:[1,0]
	v_pk_mul_f32 v[10:11], v[34:35], v[22:23] op_sel_hi:[1,0]
	v_pk_mul_f32 v[12:13], v[12:13], v[8:9]
	v_pk_mul_f32 v[10:11], v[10:11], v[6:7]
	global_store_dwordx4 v[76:77], v[10:13], off offset:528 nt
	s_nop 1
	v_pk_mul_f32 v[12:13], v[46:47], v[24:25] op_sel_hi:[1,0]
	v_pk_mul_f32 v[10:11], v[48:49], v[24:25] op_sel_hi:[1,0]
	v_pk_mul_f32 v[12:13], v[12:13], v[4:5]
	v_pk_mul_f32 v[10:11], v[10:11], v[2:3]
	global_store_dwordx4 v[80:81], v[10:13], off offset:512 nt
	s_nop 1
	v_pk_mul_f32 v[12:13], v[42:43], v[24:25] op_sel_hi:[1,0]
	v_pk_mul_f32 v[10:11], v[44:45], v[24:25] op_sel_hi:[1,0]
	v_pk_mul_f32 v[12:13], v[12:13], v[8:9]
	v_pk_mul_f32 v[10:11], v[10:11], v[6:7]
	global_store_dwordx4 v[80:81], v[10:13], off offset:528 nt
	s_nop 1
	v_pk_mul_f32 v[10:11], v[62:63], v[20:21] op_sel_hi:[1,0]
	v_pk_mul_f32 v[12:13], v[64:65], v[20:21] op_sel_hi:[1,0]
	v_pk_mul_f32 v[4:5], v[10:11], v[4:5]
	v_pk_mul_f32 v[2:3], v[12:13], v[2:3]
	global_store_dwordx4 v[30:31], v[2:5], off offset:512 nt
	s_nop 1
	v_pk_mul_f32 v[4:5], v[58:59], v[20:21] op_sel_hi:[1,0]
	v_pk_mul_f32 v[2:3], v[60:61], v[20:21] op_sel_hi:[1,0]
	v_pk_mul_f32 v[4:5], v[4:5], v[8:9]
	v_pk_mul_f32 v[2:3], v[2:3], v[6:7]
	global_store_dwordx4 v[30:31], v[2:5], off offset:528 nt
